# phase 0 balance: workgroups carrying a rope/bias/pool-weight item hand their last row item to the transposes-only workgroups
# speedup vs baseline: 1.0035x; 1.0035x over previous
.LBB0_7:
	s_or_b64 exec, exec, s[2:3]
	s_add_u32 s2, s70, 0x20000
	s_addc_u32 s3, s71, 0
	v_writelane_b32 v253, s2, 53
	s_add_u32 s94, s68, 0x100000
	s_addc_u32 s95, s69, 0
	v_writelane_b32 v253, s3, 54
	v_writelane_b32 v253, s64, 55
	v_lshlrev_b32_e32 v69, 4, v178
	v_and_b32_e32 v228, 48, v69
	v_writelane_b32 v253, s65, 56
	v_writelane_b32 v253, s66, 57
	v_writelane_b32 v252, s73, 0
	v_writelane_b32 v253, s67, 58
	v_writelane_b32 v252, s74, 1
	v_writelane_b32 v253, s68, 59
	v_writelane_b32 v252, s75, 2
	v_lshlrev_b32_e32 v2, 2, v178
	v_lshrrev_b32_e32 v175, 8, v178
	s_movk_i32 s2, 0x4100
	v_mul_u32_u24_e32 v5, 0x41, v228
	v_writelane_b32 v253, s69, 60
	v_writelane_b32 v252, s76, 3
	v_mad_u32_u24 v3, v175, s2, 0
	v_bfe_u32 v160, v178, 4, 4
	v_and_b32_e32 v221, 60, v2
	v_and_b32_e32 v4, 0xfc, v178
	v_lshlrev_b32_e32 v5, 2, v5
	v_writelane_b32 v253, s70, 61
	v_writelane_b32 v252, s77, 4
	s_cmpk_gt_i32 s62, 0x71f
	s_mov_b32 s35, 0
	v_lshl_add_u32 v222, v221, 2, v3
	v_mul_u32_u24_e32 v223, 0x104, v160
	v_or_b32_e32 v224, 16, v160
	v_or_b32_e32 v225, 32, v160
	v_or_b32_e32 v226, 48, v160
	v_bfe_u32 v227, v178, 2, 6
	v_add3_u32 v229, v3, v4, v5
	v_add3_u32 v230, v3, v5, v4
	v_mov_b32_e32 v67, 0
	v_and_b32_e32 v231, 31, v178
	v_lshrrev_b32_e32 v161, 5, v178
	v_mbcnt_lo_u32_b32 v220, -1, 0
	v_writelane_b32 v253, s71, 62
	v_writelane_b32 v252, s78, 5
	v_writelane_b32 v253, s72, 63
	v_writelane_b32 v252, s79, 6
	s_cbranch_scc1 .LBB0_96
	v_lshlrev_b32_e32 v3, 1, v178
	v_and_b32_e32 v3, 14, v3
	v_cvt_f32_ubyte0_e32 v3, v3
	v_mul_f32_e32 v3, 0xbd800000, v3
	v_mov_b32_e32 v4, 0x48f42400
	v_cmp_eq_f32_e32 vcc, 0, v3
	s_mov_b32 s2, 0x3f2aaaab
	s_movk_i32 s18, 0x204
	v_cndmask_b32_e64 v14, v4, 1.0, vcc
	v_frexp_mant_f32_e32 v4, v14
	v_cmp_gt_f32_e64 s[2:3], s2, v4
	s_mov_b32 s5, 0x42b17218
	s_mov_b32 s4, 0x7f800000
	v_cndmask_b32_e64 v5, 1.0, 2.0, s[2:3]
	v_mul_f32_e32 v4, v4, v5
	v_add_f32_e32 v7, 1.0, v4
	v_rcp_f32_e32 v12, v7
	v_add_f32_e32 v5, -1.0, v7
	v_sub_f32_e32 v9, v4, v5
	v_add_f32_e32 v5, -1.0, v4
	v_mul_f32_e32 v13, v5, v12
	v_mul_f32_e32 v6, v7, v13
	v_fma_f32 v8, v13, v7, -v6
	v_fmac_f32_e32 v8, v13, v9
	v_add_f32_e32 v4, v6, v8
	v_sub_f32_e32 v7, v5, v4
	v_pk_add_f32 v[10:11], v[4:5], v[6:7] neg_lo:[0,1] neg_hi:[0,1]
	v_mov_b32_e32 v9, v4
	v_pk_add_f32 v[4:5], v[10:11], v[8:9] neg_lo:[0,1] neg_hi:[0,1]
	v_mov_b32_e32 v8, 0x3e91f4c4
	v_add_f32_e32 v4, v4, v5
	v_add_f32_e32 v4, v7, v4
	v_mul_f32_e32 v5, v12, v4
	v_add_f32_e32 v4, v13, v5
	v_sub_f32_e32 v6, v4, v13
	v_sub_f32_e32 v15, v5, v6
	v_mul_f32_e32 v5, v4, v4
	v_fma_f32 v7, v4, v4, -v5
	v_add_f32_e32 v6, v15, v15
	v_fmac_f32_e32 v7, v4, v6
	v_add_f32_e32 v6, v5, v7
	v_fmac_f32_e32 v8, 0x3e76c4e1, v6
	v_fmaak_f32 v8, v6, v8, 0x3ecccdef
	v_sub_f32_e32 v5, v6, v5
	v_sub_f32_e32 v16, v7, v5
	v_mul_f32_e32 v5, v6, v8
	v_fma_f32 v7, v6, v8, -v5
	v_fmac_f32_e32 v7, v16, v8
	v_add_f32_e32 v8, v5, v7
	v_add_f32_e32 v9, 0x3f2aaaaa, v8
	v_sub_f32_e32 v5, v8, v5
	v_sub_f32_e32 v5, v7, v5
	v_add_f32_e32 v7, 0xbf2aaaaa, v9
	v_add_f32_e32 v5, 0x31739010, v5
	v_sub_f32_e32 v7, v8, v7
	v_pk_mul_f32 v[10:11], v[4:5], v[6:7]
	v_pk_add_f32 v[12:13], v[4:5], v[6:7]
	v_fma_f32 v8, v6, v4, -v10
	v_fmac_f32_e32 v8, v6, v15
	v_mov_b32_e32 v11, v13
	v_fmac_f32_e32 v8, v16, v4
	v_pk_add_f32 v[6:7], v[10:11], v[8:9]
	v_ldexp_f32 v16, v15, 1
	v_sub_f32_e32 v5, v6, v10
	v_sub_f32_e32 v5, v8, v5
	v_sub_f32_e32 v8, v9, v7
	v_add_f32_e32 v11, v13, v8
	v_pk_mul_f32 v[8:9], v[6:7], v[6:7] op_sel:[0,1] op_sel_hi:[1,0]
	v_cvt_f64_f32_e32 v[12:13], v14
	v_frexp_exp_i32_f64_e32 v9, v[12:13]
	v_subbrev_co_u32_e64 v9, s[2:3], 0, v9, s[2:3]
	v_cvt_f32_i32_e32 v9, v9
	v_fma_f32 v10, v6, v7, -v8
	v_fmac_f32_e32 v10, v6, v11
	s_mov_b32 s2, 0x3f317218
	v_mul_f32_e32 v6, 0x3f317218, v9
	v_fmac_f32_e32 v10, v5, v7
	v_fma_f32 v5, v9, s2, -v6
	v_fmamk_f32 v12, v9, 0xb102e308, v5
	v_ldexp_f32 v13, v4, 1
	v_add_f32_e32 v7, v8, v10
	v_pk_add_f32 v[4:5], v[6:7], v[12:13]
	v_mov_b32_e32 v14, v7
	v_mov_b32_e32 v15, v5
	v_mov_b32_e32 v9, v13
	v_pk_add_f32 v[8:9], v[14:15], v[8:9] neg_lo:[0,1] neg_hi:[0,1]
	v_mov_b32_e32 v11, v7
	v_pk_add_f32 v[8:9], v[10:11], v[8:9] neg_lo:[0,1] neg_hi:[0,1]
	v_mov_b32_e32 v13, v4
	v_add_f32_e32 v7, v16, v8
	v_add_f32_e32 v7, v7, v9
	v_pk_add_f32 v[8:9], v[4:5], v[6:7] neg_lo:[0,1] neg_hi:[0,1]
	v_pk_add_f32 v[10:11], v[4:5], v[6:7]
	v_mov_b32_e32 v6, v7
	v_mov_b32_e32 v9, v11
	v_pk_add_f32 v[14:15], v[12:13], v[8:9] neg_lo:[0,1] neg_hi:[0,1]
	v_pk_add_f32 v[8:9], v[12:13], v[8:9]
	v_mov_b32_e32 v7, v4
	v_pk_add_f32 v[12:13], v[8:9], v[4:5] op_sel:[1,0] op_sel_hi:[0,1] neg_lo:[0,1] neg_hi:[0,1]
	v_pk_add_f32 v[16:17], v[10:11], v[12:13] op_sel_hi:[1,0] neg_lo:[0,1] neg_hi:[0,1]
	v_mov_b32_e32 v10, v11
	v_mov_b32_e32 v11, v9
	v_pk_mov_b32 v[12:13], v[4:5], v[12:13] op_sel:[1,0]
	v_mov_b32_e32 v16, v14
	v_pk_add_f32 v[10:11], v[10:11], v[12:13] neg_lo:[0,1] neg_hi:[0,1]
	v_mov_b32_e32 v15, v9
	v_pk_add_f32 v[4:5], v[6:7], v[10:11] neg_lo:[0,1] neg_hi:[0,1]
	s_load_dwordx16 s[36:51], s[0:1], 0x0
	v_pk_add_f32 v[6:7], v[16:17], v[4:5]
	s_load_dwordx16 s[64:79], s[0:1], 0x80
	v_pk_add_f32 v[10:11], v[6:7], v[6:7] op_sel:[0,1] op_sel_hi:[1,0]
	v_and_b32_e32 v70, 63, v178
	v_pk_add_f32 v[8:9], v[8:9], v[10:11] op_sel:[1,0] op_sel_hi:[0,1]
	v_mov_b32_e32 v7, v8
	v_pk_add_f32 v[12:13], v[6:7], v[14:15] neg_lo:[0,1] neg_hi:[0,1]
	v_mov_b32_e32 v5, v10
	v_sub_f32_e32 v6, v6, v12
	v_pk_add_f32 v[4:5], v[4:5], v[12:13] neg_lo:[0,1] neg_hi:[0,1]
	v_sub_f32_e32 v6, v14, v6
	v_add_f32_e32 v4, v4, v6
	v_add_f32_e32 v4, v4, v5
	v_add_f32_e32 v5, v8, v4
	v_sub_f32_e32 v6, v5, v8
	v_sub_f32_e32 v4, v4, v6
	v_mul_f32_e32 v6, v3, v5
	v_fma_f32 v5, v3, v5, -v6
	v_fmac_f32_e32 v5, v3, v4
	v_add_f32_e32 v4, v6, v5
	v_cmp_class_f32_e64 s[2:3], v6, s18
	v_sub_f32_e32 v7, v4, v6
	v_sub_f32_e32 v5, v5, v7
	v_cndmask_b32_e64 v4, v4, v6, s[2:3]
	v_mov_b32_e32 v6, 0x37000000
	v_cmp_eq_f32_e64 s[2:3], s5, v4
	v_lshlrev_b32_e32 v66, 4, v70
	s_waitcnt lgkmcnt(0)
	v_lshl_add_u64 v[72:73], s[36:37], 0, v[66:67]
	v_cndmask_b32_e64 v6, 0, v6, s[2:3]
	v_sub_f32_e32 v7, v4, v6
	s_mov_b32 s2, 0x3fb8aa3b
	v_mul_f32_e32 v8, 0x3fb8aa3b, v7
	v_fma_f32 v9, v7, s2, -v8
	v_rndne_f32_e32 v10, v8
	v_fmamk_f32 v9, v7, 0x32a5705f, v9
	v_sub_f32_e32 v8, v8, v10
	v_add_f32_e32 v8, v8, v9
	v_exp_f32_e32 v8, v8
	v_cvt_i32_f32_e32 v9, v10
	v_cmp_neq_f32_e64 s[2:3], |v4|, s4
	v_lshlrev_b32_e32 v66, 3, v70
	v_lshl_add_u64 v[74:75], s[70:71], 0, v[66:67]
	v_cndmask_b32_e64 v4, 0, v5, s[2:3]
	s_mov_b32 s2, 0xc2ce8ed0
	v_ldexp_f32 v5, v8, v9
	v_cmp_ngt_f32_e64 s[2:3], s2, v7
	v_add_f32_e32 v4, v6, v4
	v_mov_b32_e32 v6, 0x7f800000
	v_cndmask_b32_e64 v5, 0, v5, s[2:3]
	v_cmp_nlt_f32_e64 s[2:3], s5, v7
	s_load_dwordx16 s[64:79], s[0:1], 0xc0
	v_and_b32_e32 v87, 0x7f, v178
	v_cndmask_b32_e64 v5, v6, v5, s[2:3]
	v_fma_f32 v4, v5, v4, v5
	v_cmp_class_f32_e64 s[2:3], v5, s18
	v_lshl_add_u32 v68, v87, 2, 0
	s_lshl_b32 s12, s62, 5
	v_cndmask_b32_e64 v4, v4, v5, s[2:3]
	v_cmp_neq_f32_e64 s[2:3], v3, |v3|
	v_or_b32_e32 v71, 0xfff24000, v178
	v_lshl_add_u32 v89, v87, 9, v68
	v_cndmask_b32_e64 v5, v6, 0, s[2:3]
	v_cndmask_b32_e64 v5, v5, 1.0, vcc
	v_cmp_class_f32_e64 s[2:3], v3, s18
	v_and_b32_e32 v3, 0xf80, v2
	v_or_b32_e32 v90, 0x800, v87
	v_cndmask_b32_e64 v86, |v4|, v5, s[2:3]
	v_lshrrev_b32_e32 v5, 3, v178
	v_and_b32_e32 v88, 0x70, v5
	v_lshrrev_b32_e32 v5, 4, v178
	v_and_b32_e32 v103, 60, v5
	v_lshrrev_b32_e32 v5, 9, v178
	v_sub_u32_e32 v6, 32, v5
	v_sub_u32_e32 v5, 30, v5
	v_or_b32_e32 v4, 0x7f, v2
	v_lshrrev_b32_e32 v5, 1, v5
	v_add_u32_e32 v2, 0, v2
	v_add_u32_e32 v5, 1, v5
	v_and_b32_e32 v7, 62, v6
	v_sub_u32_e32 v3, v4, v3
	v_add_u32_e32 v111, 0x10200, v2
	v_lshrrev_b32_e32 v2, 1, v178
	v_and_b32_e32 v104, 3, v5
	v_add_u32_e32 v106, 1, v3
	v_lshrrev_b32_e32 v3, 5, v178
	v_lshlrev_b32_e32 v4, 2, v231
	v_lshl_or_b32 v107, v7, 9, v178
	v_and_b32_e32 v2, 0x1c0, v2
	v_cmp_gt_u32_e64 s[2:3], 32, v178
	v_or_b32_e32 v91, 0xa00, v87
	v_or_b32_e32 v92, 0xc00, v87
	v_or_b32_e32 v93, 0xe00, v87
	v_or_b32_e32 v94, 0x1000, v87
	v_or_b32_e32 v95, 0x1200, v87
	v_or_b32_e32 v96, 0x1400, v87
	v_or_b32_e32 v97, 0x1600, v87
	v_or_b32_e32 v98, 0x1800, v87
	v_or_b32_e32 v99, 0x1a00, v87
	v_or_b32_e32 v100, 0x1c00, v87
	v_or_b32_e32 v101, 0x1e00, v87
	v_or_b32_e32 v102, 0xfffff800, v175
	v_cmp_eq_u32_e64 s[4:5], 0, v70
	s_sub_i32 s19, 0x71f, s62
	v_add_u32_e32 v179, 0x200, v178
	v_and_b32_e32 v105, 28, v5
	v_cmp_ne_u32_e64 s[6:7], 0, v104
	v_cmp_ne_u32_e64 s[8:9], v6, v7
	v_lshlrev_b32_e32 v76, 9, v3
	v_mov_b32_e32 v77, v67
	v_lshl_or_b32 v78, v3, 17, v4
	v_mov_b32_e32 v79, v67
	s_sub_i32 s20, 0x9e0, s12
	s_lshl_b32 s21, s92, 5
	v_add_u32_e32 v108, 0xfffffe00, v107
	s_sub_i32 s22, 0x8f, s62
	v_lshrrev_b32_e32 v109, 7, v107
	v_add_u32_e32 v110, 0xfffffe00, v178
	v_add_u32_e32 v112, 0, v2
	s_mov_b32 s23, 0x800000
	v_mov_b32_e32 v113, 0x3c0881c4
	v_mov_b32_e32 v114, 0xbab64f3b
	v_mov_b32_e32 v115, 0x358637bd
	v_not_b32_e32 v116, 63
	v_not_b32_e32 v117, 31
	v_mov_b32_e32 v118, 0x7fc00000
	v_mbcnt_hi_u32_b32 v119, -1, v220
	s_mov_b32 s98, 0
	s_mov_b32 s99, 0
	s_cmp_lg_u32 s92, 0x100
	s_cbranch_scc1 .Lp0r_i
	s_cmp_lt_u32 s62, 32
	s_cbranch_scc1 .Lp0r_i
	s_movk_i32 s98, 0x100
	s_cmp_lt_u32 s62, 144
	s_cbranch_scc1 .Lp0r_i
	s_mov_b32 s98, 0
	s_mov_b32 s99, 1
.Lp0r_i:
	s_branch .LBB0_11
.LBB0_9:
	s_or_b64 exec, exec, s[12:13]
	v_lshlrev_b32_e32 v66, 1, v82
	v_cvt_pk_bf16_f32 v14, v14, v15
	v_cvt_pk_bf16_f32 v15, v16, v17
	v_lshl_add_u64 v[16:17], v[74:75], 0, v[66:67]
	v_cvt_pk_bf16_f32 v10, v10, v11
	v_cvt_pk_bf16_f32 v11, v12, v13
	v_cvt_pk_bf16_f32 v6, v6, v7
	v_cvt_pk_bf16_f32 v7, v8, v9
	v_cvt_pk_bf16_f32 v2, v2, v3
	v_cvt_pk_bf16_f32 v3, v4, v5
	global_store_dwordx2 v[16:17], v[14:15], off
	global_store_dwordx2 v[16:17], v[10:11], off offset:512
	global_store_dwordx2 v[16:17], v[6:7], off offset:1024
	global_store_dwordx2 v[16:17], v[2:3], off offset:1536
.LBB0_10:
	s_sub_i32 s19, s19, s92
	s_sub_i32 s20, s20, s21
	s_sub_i32 s22, s22, s92
	s_cmp_lt_i32 s19, s98
	s_cbranch_scc0 .LBB0_11
	s_cmp_eq_u32 s99, 1
	s_cbranch_scc0 .LBB0_96
	s_mov_b32 s99, 0
	s_mov_b32 s98, 0
	s_mov_b32 s19, s62
	s_lshl_b32 s20, s19, 5
	s_add_i32 s20, s20, 0xffff2600
	s_add_i32 s22, s19, 0xfffff970
